# local seams: fire-and-forget arrival atomic + every workgroup polls the per-XCD arrival counter (no returned atomic, no leader/generation hop)
# speedup vs baseline: 1.0010x; 1.0010x over previous
; DI unsigned xb_ld(unsigned* p) { return __hip_atomic_load(p, __ATOMIC_RELAXED, __HIP_MEMORY_SCOPE_AGENT); }
; DI unsigned xb_add(unsigned* p, unsigned v) { return __hip_atomic_fetch_add(p, v, __ATOMIC_RELAXED, __HIP_MEMORY_SCOPE_AGENT); }
; #define XB_SPIN(cond, bar) do { unsigned _sp = 0; while (cond) { __builtin_amdgcn_s_sleep(1); \
;     if ((++_sp & 255u) == 0u) { if (xb_ld(&(bar)[XB_TMO])) break; if (_sp > XB_SPIN_CAP) { atomicAdd(&(bar)[XB_TMO], 1u); break; } } } } while (0)
; DI void xcd_barrier(const XcdBarrier& b) {
;   asm volatile("s_waitcnt vmcnt(0)" ::: "memory");
;   __syncthreads();
;   if (threadIdx.x == 0) {
;     unsigned* bar = b.bar;
;     __builtin_amdgcn_s_waitcnt(0);
;     unsigned nloc = b.st[0], nx = b.st[1];
;     if (nloc == 0u) { xcd_barrier_complete(bar, b.x, nloc, nx); b.st[0] = nloc; b.st[1] = nx; }
;     const unsigned old = xb_add(&bar[XB_XSUB(b.x)], 1u);
;     const unsigned gen = old / nloc;
;     if (old + 1u == (gen + 1u) * nloc) {
;       __builtin_amdgcn_fence(__ATOMIC_RELEASE, "agent");
;       asm volatile("s_waitcnt vmcnt(0)" ::: "memory");
;       const unsigned og = xb_add(&bar[XB_TOP], 1u);
;       const unsigned tg = og / nx;
;       if (og + 1u == (tg + 1u) * nx) xb_add(&bar[XB_TOPGEN], 1u);
;       else XB_SPIN(xb_ld(&bar[XB_TOPGEN]) == tg, bar);
;       __builtin_amdgcn_fence(__ATOMIC_ACQUIRE, "agent");
;       xb_add(&bar[XB_XGEN(b.x)], 1u);
;       asm volatile("s_waitcnt vmcnt(0)" ::: "memory");
;     } else {
;       XB_SPIN(xb_ld(&bar[XB_XGEN(b.x)]) == gen, bar);
;       __builtin_amdgcn_fence(__ATOMIC_ACQUIRE, "agent");
;       asm volatile("s_waitcnt vmcnt(0)" ::: "memory");
;     }
;   }
;   __syncthreads();
; }
.LBB0_377:
	s_waitcnt vmcnt(0)
	s_waitcnt vmcnt(0)
	s_barrier
	s_mov_b64 s[0:1], exec
	v_readlane_b32 s4, v254, 8
	v_readlane_b32 s5, v254, 9
	s_and_b64 s[4:5], s[0:1], s[4:5]
	s_mov_b64 exec, s[4:5]
	s_cbranch_execz .LBB0_429
	v_mov_b32_e32 v1, 0
	ds_read_b32 v3, v1 offset:264
	s_waitcnt lgkmcnt(0)
	v_readfirstlane_b32 s100, v3
	s_nop 3
	s_cmp_lg_u32 s100, 0
	s_cbranch_scc0 .Lfp_fb_2
	buffer_inv sc1
	ds_read_b32 v3, v1 offset:256
	v_readlane_b32 s100, v254, 5
	s_waitcnt lgkmcnt(0)
	v_readfirstlane_b32 s101, v3
	s_nop 3
	s_mul_i32 s101, s101, 2
	s_lshl_b32 s100, s100, 8
	s_add_i32 s100, s100, 0xbfa1400
	v_mov_b32_e32 v1, s100
	v_mov_b32_e32 v3, 1
	global_atomic_add v1, v3, s[86:87]
.Lfp_spin_2:
	global_load_dword v3, v1, s[86:87] sc1
	s_waitcnt vmcnt(0)
	v_readfirstlane_b32 s100, v3
	s_nop 3
	s_cmp_ge_u32 s100, s101
	s_cbranch_scc1 .Lfp_done_2
	s_sleep 1
	s_branch .Lfp_spin_2

; DI unsigned xb_ld(unsigned* p) { return __hip_atomic_load(p, __ATOMIC_RELAXED, __HIP_MEMORY_SCOPE_AGENT); }
; DI void xcd_barrier_complete(unsigned* bar, unsigned x, unsigned& nloc, unsigned& nx) {
;   const unsigned G = gridDim.x * gridDim.y * gridDim.z;
;   unsigned sum, cnt, mine, sp = 0u;
;   for (;;) {
;     sum = 0u; cnt = 0u; mine = 0u;
; #pragma unroll
;     for (unsigned j = 0; j < 16; ++j) { const unsigned c = xb_ld(&bar[XB_XCNT(j)]); sum += c; cnt += (c > 0u) ? 1u : 0u; mine = (j == x) ? c : mine; }
; DI void xcd_barrier(const XcdBarrier& b) {
;     ...
;   if (threadIdx.x == 0) {
;     unsigned* bar = b.bar;
;     __builtin_amdgcn_s_waitcnt(0);
;     unsigned nloc = b.st[0], nx = b.st[1];
;     if (nloc == 0u) { xcd_barrier_complete(bar, b.x, nloc, nx); b.st[0] = nloc; b.st[1] = nx; }
.Lfp_fb_2:
	v_mov_b32_e32 v1, 0
	s_waitcnt vmcnt(0) expcnt(0) lgkmcnt(0)
	ds_read_b32 v3, v1 offset:256
	ds_read_b32 v2, v1 offset:260
	s_waitcnt lgkmcnt(1)
	v_cmp_ne_u32_e32 vcc, 0, v3
	s_cbranch_vccnz .LBB0_393
	v_readlane_b32 s4, v254, 4
	s_mul_i32 s16, s89, s4
	s_add_u32 s4, s86, 0xbfa0200
	s_addc_u32 s5, s87, 0
	s_add_u32 s6, s86, 0xbfa0400
	s_addc_u32 s7, s87, 0
	s_add_u32 s8, s86, 0xbfa0500
	s_addc_u32 s9, s87, 0
	s_add_u32 s10, s86, 0xbfa0600
	s_addc_u32 s11, s87, 0
	s_add_u32 s12, s86, 0xbfa0700
	s_addc_u32 s13, s87, 0
	s_add_u32 s14, s86, 0xbfa0800
	s_addc_u32 s15, s87, 0
	s_add_u32 s18, s86, 0xbfa0900
	s_addc_u32 s19, s87, 0
	s_add_u32 s20, s86, 0xbfa0a00
	s_addc_u32 s21, s87, 0
	s_add_u32 s22, s86, 0xbfa0b00
	s_addc_u32 s23, s87, 0
	s_add_u32 s24, s86, 0xbfa0c00
	s_addc_u32 s25, s87, 0
	s_add_u32 s26, s86, 0xbfa0d00
	s_addc_u32 s27, s87, 0
	s_add_u32 s28, s86, 0xbfa0e00
	s_addc_u32 s29, s87, 0
	s_add_u32 s30, s86, 0xbfa0f00
	s_addc_u32 s31, s87, 0
	s_add_u32 s34, s86, 0xbfa1000
	s_addc_u32 s35, s87, 0
	s_add_u32 s36, s86, 0xbfa1100
	s_addc_u32 s37, s87, 0
	s_add_u32 s38, s86, 0xbfa1200
	s_addc_u32 s39, s87, 0
	s_add_u32 s40, s86, 0xbfa1300
	s_mul_i32 s16, s16, s88
	s_addc_u32 s41, s87, 0
	s_mov_b32 s17, 1
	s_branch .LBB0_381

; DI unsigned xb_ld(unsigned* p) { return __hip_atomic_load(p, __ATOMIC_RELAXED, __HIP_MEMORY_SCOPE_AGENT); }
; DI unsigned xb_add(unsigned* p, unsigned v) { return __hip_atomic_fetch_add(p, v, __ATOMIC_RELAXED, __HIP_MEMORY_SCOPE_AGENT); }
; #define XB_SPIN(cond, bar) do { unsigned _sp = 0; while (cond) { __builtin_amdgcn_s_sleep(1); \
;     if ((++_sp & 255u) == 0u) { if (xb_ld(&(bar)[XB_TMO])) break; if (_sp > XB_SPIN_CAP) { atomicAdd(&(bar)[XB_TMO], 1u); break; } } } } while (0)
; DI void xcd_barrier(const XcdBarrier& b) {
;   asm volatile("s_waitcnt vmcnt(0)" ::: "memory");
;   __syncthreads();
;   if (threadIdx.x == 0) {
;     unsigned* bar = b.bar;
;     __builtin_amdgcn_s_waitcnt(0);
;     unsigned nloc = b.st[0], nx = b.st[1];
;     if (nloc == 0u) { xcd_barrier_complete(bar, b.x, nloc, nx); b.st[0] = nloc; b.st[1] = nx; }
;     const unsigned old = xb_add(&bar[XB_XSUB(b.x)], 1u);
;     const unsigned gen = old / nloc;
;     if (old + 1u == (gen + 1u) * nloc) {
;       __builtin_amdgcn_fence(__ATOMIC_RELEASE, "agent");
;       asm volatile("s_waitcnt vmcnt(0)" ::: "memory");
;       const unsigned og = xb_add(&bar[XB_TOP], 1u);
;       const unsigned tg = og / nx;
;       if (og + 1u == (tg + 1u) * nx) xb_add(&bar[XB_TOPGEN], 1u);
;       else XB_SPIN(xb_ld(&bar[XB_TOPGEN]) == tg, bar);
;       __builtin_amdgcn_fence(__ATOMIC_ACQUIRE, "agent");
;       xb_add(&bar[XB_XGEN(b.x)], 1u);
;       asm volatile("s_waitcnt vmcnt(0)" ::: "memory");
;     } else {
;       XB_SPIN(xb_ld(&bar[XB_XGEN(b.x)]) == gen, bar);
;       __builtin_amdgcn_fence(__ATOMIC_ACQUIRE, "agent");
;       asm volatile("s_waitcnt vmcnt(0)" ::: "memory");
;     }
;   }
;   __syncthreads();
; }
.LBB0_500:
	s_waitcnt vmcnt(0)
	s_barrier
	s_mov_b64 s[0:1], exec
	v_readlane_b32 s2, v254, 8
	v_readlane_b32 s3, v254, 9
	s_and_b64 s[2:3], s[0:1], s[2:3]
	s_mov_b64 exec, s[2:3]
	s_cbranch_execz .LBB0_552
	v_mov_b32_e32 v0, 0
	ds_read_b32 v2, v0 offset:264
	s_waitcnt lgkmcnt(0)
	v_readfirstlane_b32 s100, v2
	s_nop 3
	s_cmp_lg_u32 s100, 0
	s_cbranch_scc0 .Lfp_fb_3
	buffer_inv sc1
	ds_read_b32 v2, v0 offset:256
	v_readlane_b32 s100, v254, 5
	s_waitcnt lgkmcnt(0)
	v_readfirstlane_b32 s101, v2
	s_nop 3
	s_mul_i32 s101, s101, 3
	s_lshl_b32 s100, s100, 8
	s_add_i32 s100, s100, 0xbfa1400
	v_mov_b32_e32 v0, s100
	v_mov_b32_e32 v2, 1
	global_atomic_add v0, v2, s[86:87]
.Lfp_spin_3:
	global_load_dword v2, v0, s[86:87] sc1
	s_waitcnt vmcnt(0)
	v_readfirstlane_b32 s100, v2
	s_nop 3
	s_cmp_ge_u32 s100, s101
	s_cbranch_scc1 .Lfp_done_3
	s_sleep 1
	s_branch .Lfp_spin_3
.Lfp_done_3:
	v_readlane_b32 s100, v254, 20
	s_nop 3
	s_cmp_lt_u32 s100, 8
	s_cbranch_scc0 .Lfp_na_3
	v_mov_b32_e32 v0, 0xbfa0208
	v_mov_b32_e32 v2, 1
	global_atomic_add v0, v2, s[86:87]
	s_waitcnt vmcnt(0)

; DI unsigned xb_ld(unsigned* p) { return __hip_atomic_load(p, __ATOMIC_RELAXED, __HIP_MEMORY_SCOPE_AGENT); }
; DI void xcd_barrier_complete(unsigned* bar, unsigned x, unsigned& nloc, unsigned& nx) {
;   const unsigned G = gridDim.x * gridDim.y * gridDim.z;
;   unsigned sum, cnt, mine, sp = 0u;
;   for (;;) {
;     sum = 0u; cnt = 0u; mine = 0u;
; #pragma unroll
;     for (unsigned j = 0; j < 16; ++j) { const unsigned c = xb_ld(&bar[XB_XCNT(j)]); sum += c; cnt += (c > 0u) ? 1u : 0u; mine = (j == x) ? c : mine; }
; DI void xcd_barrier(const XcdBarrier& b) {
;     ...
;   if (threadIdx.x == 0) {
;     unsigned* bar = b.bar;
;     __builtin_amdgcn_s_waitcnt(0);
;     unsigned nloc = b.st[0], nx = b.st[1];
;     if (nloc == 0u) { xcd_barrier_complete(bar, b.x, nloc, nx); b.st[0] = nloc; b.st[1] = nx; }
.Lfp_fb_3:
	v_mov_b32_e32 v0, 0
	s_waitcnt vmcnt(0) expcnt(0) lgkmcnt(0)
	ds_read_b32 v2, v0 offset:256
	ds_read_b32 v1, v0 offset:260
	s_waitcnt lgkmcnt(1)
	v_cmp_ne_u32_e32 vcc, 0, v2
	s_cbranch_vccnz .LBB0_516
	s_add_u32 s4, s86, 0xbfa0200
	s_addc_u32 s5, s87, 0
	s_add_u32 s6, s86, 0xbfa0400
	s_addc_u32 s7, s87, 0
	s_add_u32 s8, s86, 0xbfa0500
	s_addc_u32 s9, s87, 0
	s_add_u32 s10, s86, 0xbfa0600
	s_addc_u32 s11, s87, 0
	s_add_u32 s12, s86, 0xbfa0700
	s_addc_u32 s13, s87, 0
	s_add_u32 s14, s86, 0xbfa0800
	s_addc_u32 s15, s87, 0
	s_add_u32 s18, s86, 0xbfa0900
	s_addc_u32 s19, s87, 0
	s_add_u32 s20, s86, 0xbfa0a00
	s_addc_u32 s21, s87, 0
	s_add_u32 s22, s86, 0xbfa0b00
	s_addc_u32 s23, s87, 0
	s_add_u32 s24, s86, 0xbfa0c00
	s_addc_u32 s25, s87, 0
	s_add_u32 s26, s86, 0xbfa0d00
	s_addc_u32 s27, s87, 0
	s_add_u32 s28, s86, 0xbfa0e00
	s_addc_u32 s29, s87, 0
	s_add_u32 s30, s86, 0xbfa0f00
	s_addc_u32 s31, s87, 0
	s_add_u32 s34, s86, 0xbfa1000
	s_addc_u32 s35, s87, 0
	s_add_u32 s36, s86, 0xbfa1100
	s_addc_u32 s37, s87, 0
	s_add_u32 s38, s86, 0xbfa1200
	v_readlane_b32 s2, v254, 4
	s_addc_u32 s39, s87, 0
	s_mul_i32 s2, s89, s2
	s_add_u32 s40, s86, 0xbfa1300
	s_mul_i32 s2, s2, s88
	s_addc_u32 s41, s87, 0
	s_mov_b32 s3, 1
	s_branch .LBB0_504

; DI unsigned xb_ld(unsigned* p) { return __hip_atomic_load(p, __ATOMIC_RELAXED, __HIP_MEMORY_SCOPE_AGENT); }
; DI unsigned xb_add(unsigned* p, unsigned v) { return __hip_atomic_fetch_add(p, v, __ATOMIC_RELAXED, __HIP_MEMORY_SCOPE_AGENT); }
; #define XB_SPIN(cond, bar) do { unsigned _sp = 0; while (cond) { __builtin_amdgcn_s_sleep(1); \
;     if ((++_sp & 255u) == 0u) { if (xb_ld(&(bar)[XB_TMO])) break; if (_sp > XB_SPIN_CAP) { atomicAdd(&(bar)[XB_TMO], 1u); break; } } } } while (0)
; DI void xcd_barrier(const XcdBarrier& b) {
;   asm volatile("s_waitcnt vmcnt(0)" ::: "memory");
;   __syncthreads();
;   if (threadIdx.x == 0) {
;     unsigned* bar = b.bar;
;     __builtin_amdgcn_s_waitcnt(0);
;     unsigned nloc = b.st[0], nx = b.st[1];
;     if (nloc == 0u) { xcd_barrier_complete(bar, b.x, nloc, nx); b.st[0] = nloc; b.st[1] = nx; }
;     const unsigned old = xb_add(&bar[XB_XSUB(b.x)], 1u);
;     const unsigned gen = old / nloc;
;     if (old + 1u == (gen + 1u) * nloc) {
;       __builtin_amdgcn_fence(__ATOMIC_RELEASE, "agent");
;       asm volatile("s_waitcnt vmcnt(0)" ::: "memory");
;       const unsigned og = xb_add(&bar[XB_TOP], 1u);
;       const unsigned tg = og / nx;
;       if (og + 1u == (tg + 1u) * nx) xb_add(&bar[XB_TOPGEN], 1u);
;       else XB_SPIN(xb_ld(&bar[XB_TOPGEN]) == tg, bar);
;       __builtin_amdgcn_fence(__ATOMIC_ACQUIRE, "agent");
;       xb_add(&bar[XB_XGEN(b.x)], 1u);
;       asm volatile("s_waitcnt vmcnt(0)" ::: "memory");
;     } else {
;       XB_SPIN(xb_ld(&bar[XB_XGEN(b.x)]) == gen, bar);
;       __builtin_amdgcn_fence(__ATOMIC_ACQUIRE, "agent");
;       asm volatile("s_waitcnt vmcnt(0)" ::: "memory");
;     }
;   }
;   __syncthreads();
; }
.LBB0_586:
	s_waitcnt vmcnt(0)
	s_waitcnt lgkmcnt(0)
	s_barrier
	s_mov_b64 s[0:1], exec
	v_readlane_b32 s2, v254, 8
	v_readlane_b32 s3, v254, 9
	v_readlane_b32 s96, v254, 18
	s_and_b64 s[2:3], s[0:1], s[2:3]
	v_readlane_b32 s78, v254, 5
	v_readlane_b32 s97, v254, 19
	s_mov_b64 exec, s[2:3]
	s_cbranch_execz .LBB0_638
	v_mov_b32_e32 v0, 0
	ds_read_b32 v2, v0 offset:264
	s_waitcnt lgkmcnt(0)
	v_readfirstlane_b32 s100, v2
	s_nop 3
	s_cmp_lg_u32 s100, 0
	s_cbranch_scc0 .Lfp_fb_4
	buffer_inv sc1
	ds_read_b32 v2, v0 offset:256
	v_readlane_b32 s100, v254, 5
	s_waitcnt lgkmcnt(0)
	v_readfirstlane_b32 s101, v2
	s_nop 3
	s_mul_i32 s101, s101, 4
	s_lshl_b32 s100, s100, 8
	s_add_i32 s100, s100, 0xbfa1400
	v_mov_b32_e32 v0, s100
	v_mov_b32_e32 v2, 1
	global_atomic_add v0, v2, s[86:87]

; DI unsigned xb_ld(unsigned* p) { return __hip_atomic_load(p, __ATOMIC_RELAXED, __HIP_MEMORY_SCOPE_AGENT); }
; DI unsigned xb_add(unsigned* p, unsigned v) { return __hip_atomic_fetch_add(p, v, __ATOMIC_RELAXED, __HIP_MEMORY_SCOPE_AGENT); }
; #define XB_SPIN(cond, bar) do { unsigned _sp = 0; while (cond) { __builtin_amdgcn_s_sleep(1); \
;     if ((++_sp & 255u) == 0u) { if (xb_ld(&(bar)[XB_TMO])) break; if (_sp > XB_SPIN_CAP) { atomicAdd(&(bar)[XB_TMO], 1u); break; } } } } while (0)
; DI void xcd_barrier(const XcdBarrier& b) {
;     ...
;     if (old + 1u == (gen + 1u) * nloc) {
;       __builtin_amdgcn_fence(__ATOMIC_RELEASE, "agent");
;       asm volatile("s_waitcnt vmcnt(0)" ::: "memory");
;       const unsigned og = xb_add(&bar[XB_TOP], 1u);
;       const unsigned tg = og / nx;
;       if (og + 1u == (tg + 1u) * nx) xb_add(&bar[XB_TOPGEN], 1u);
;       else XB_SPIN(xb_ld(&bar[XB_TOPGEN]) == tg, bar);
;       __builtin_amdgcn_fence(__ATOMIC_ACQUIRE, "agent");
.Lfp_done_4:
	s_min_u32 s101, s88, 8
	v_mov_b32_e32 v0, 0xbfa0208

; DI unsigned xb_ld(unsigned* p) { return __hip_atomic_load(p, __ATOMIC_RELAXED, __HIP_MEMORY_SCOPE_AGENT); }
; DI void xcd_barrier_complete(unsigned* bar, unsigned x, unsigned& nloc, unsigned& nx) {
;   const unsigned G = gridDim.x * gridDim.y * gridDim.z;
;   unsigned sum, cnt, mine, sp = 0u;
;   for (;;) {
;     sum = 0u; cnt = 0u; mine = 0u;
; #pragma unroll
;     for (unsigned j = 0; j < 16; ++j) { const unsigned c = xb_ld(&bar[XB_XCNT(j)]); sum += c; cnt += (c > 0u) ? 1u : 0u; mine = (j == x) ? c : mine; }
; DI void xcd_barrier(const XcdBarrier& b) {
;     ...
;   if (threadIdx.x == 0) {
;     unsigned* bar = b.bar;
;     __builtin_amdgcn_s_waitcnt(0);
;     unsigned nloc = b.st[0], nx = b.st[1];
;     if (nloc == 0u) { xcd_barrier_complete(bar, b.x, nloc, nx); b.st[0] = nloc; b.st[1] = nx; }
.Lfp_fb_4:
	v_mov_b32_e32 v0, 0
	s_waitcnt vmcnt(0) expcnt(0) lgkmcnt(0)
	ds_read_b32 v2, v0 offset:256
	ds_read_b32 v1, v0 offset:260
	s_waitcnt lgkmcnt(1)
	v_cmp_ne_u32_e32 vcc, 0, v2
	s_cbranch_vccnz .LBB0_602
	s_add_u32 s6, s86, 0xbfa0200
	s_addc_u32 s7, s87, 0
	s_add_u32 s8, s86, 0xbfa0400
	s_addc_u32 s9, s87, 0
	s_add_u32 s10, s86, 0xbfa0500
	s_addc_u32 s11, s87, 0
	s_add_u32 s12, s86, 0xbfa0600
	s_addc_u32 s13, s87, 0
	s_add_u32 s14, s86, 0xbfa0700
	s_addc_u32 s15, s87, 0
	s_add_u32 s18, s86, 0xbfa0800
	s_addc_u32 s19, s87, 0
	s_add_u32 s20, s86, 0xbfa0900
	s_addc_u32 s21, s87, 0
	s_add_u32 s22, s86, 0xbfa0a00
	s_addc_u32 s23, s87, 0
	s_add_u32 s24, s86, 0xbfa0b00
	s_addc_u32 s25, s87, 0
	s_add_u32 s26, s86, 0xbfa0c00
	s_addc_u32 s27, s87, 0
	s_add_u32 s28, s86, 0xbfa0d00
	s_addc_u32 s29, s87, 0
	s_add_u32 s30, s86, 0xbfa0e00
	s_addc_u32 s31, s87, 0
	s_add_u32 s34, s86, 0xbfa0f00
	s_addc_u32 s35, s87, 0
	s_add_u32 s36, s86, 0xbfa1000
	s_addc_u32 s37, s87, 0
	s_add_u32 s38, s86, 0xbfa1100
	s_addc_u32 s39, s87, 0
	s_add_u32 s40, s86, 0xbfa1200
	v_readlane_b32 s2, v254, 4
	s_addc_u32 s41, s87, 0
	s_mul_i32 s2, s89, s2
	s_add_u32 s44, s86, 0xbfa1300
	s_mul_i32 s2, s2, s88
	s_addc_u32 s45, s87, 0
	s_mov_b32 s3, 1
	s_branch .LBB0_590

; DI unsigned xb_ld(unsigned* p) { return __hip_atomic_load(p, __ATOMIC_RELAXED, __HIP_MEMORY_SCOPE_AGENT); }
; DI unsigned xb_add(unsigned* p, unsigned v) { return __hip_atomic_fetch_add(p, v, __ATOMIC_RELAXED, __HIP_MEMORY_SCOPE_AGENT); }
; #define XB_SPIN(cond, bar) do { unsigned _sp = 0; while (cond) { __builtin_amdgcn_s_sleep(1); \
;     if ((++_sp & 255u) == 0u) { if (xb_ld(&(bar)[XB_TMO])) break; if (_sp > XB_SPIN_CAP) { atomicAdd(&(bar)[XB_TMO], 1u); break; } } } } while (0)
; DI void xcd_barrier(const XcdBarrier& b) {
;   asm volatile("s_waitcnt vmcnt(0)" ::: "memory");
;   __syncthreads();
;   if (threadIdx.x == 0) {
;     unsigned* bar = b.bar;
;     __builtin_amdgcn_s_waitcnt(0);
;     unsigned nloc = b.st[0], nx = b.st[1];
;     if (nloc == 0u) { xcd_barrier_complete(bar, b.x, nloc, nx); b.st[0] = nloc; b.st[1] = nx; }
;     const unsigned old = xb_add(&bar[XB_XSUB(b.x)], 1u);
;     const unsigned gen = old / nloc;
;     if (old + 1u == (gen + 1u) * nloc) {
;       __builtin_amdgcn_fence(__ATOMIC_RELEASE, "agent");
;       asm volatile("s_waitcnt vmcnt(0)" ::: "memory");
;       const unsigned og = xb_add(&bar[XB_TOP], 1u);
;       const unsigned tg = og / nx;
;       if (og + 1u == (tg + 1u) * nx) xb_add(&bar[XB_TOPGEN], 1u);
;       else XB_SPIN(xb_ld(&bar[XB_TOPGEN]) == tg, bar);
;       __builtin_amdgcn_fence(__ATOMIC_ACQUIRE, "agent");
;       xb_add(&bar[XB_XGEN(b.x)], 1u);
;       asm volatile("s_waitcnt vmcnt(0)" ::: "memory");
;     } else {
;       XB_SPIN(xb_ld(&bar[XB_XGEN(b.x)]) == gen, bar);
;       __builtin_amdgcn_fence(__ATOMIC_ACQUIRE, "agent");
;       asm volatile("s_waitcnt vmcnt(0)" ::: "memory");
;     }
;   }
;   __syncthreads();
; }
.LBB0_654:
	s_waitcnt vmcnt(0)
	v_readlane_b32 s94, v254, 8
	v_readlane_b32 s95, v254, 9
	s_barrier
	s_and_saveexec_b64 s[0:1], s[94:95]
	s_cbranch_execz .LBB0_706
	v_mov_b32_e32 v0, 0
	ds_read_b32 v2, v0 offset:264
	s_waitcnt lgkmcnt(0)
	v_readfirstlane_b32 s100, v2
	s_nop 3
	s_cmp_lg_u32 s100, 0
	s_cbranch_scc0 .Lfp_fb_5
	buffer_inv sc1
	ds_read_b32 v2, v0 offset:256
	v_readlane_b32 s100, v254, 5
	s_waitcnt lgkmcnt(0)
	v_readfirstlane_b32 s101, v2
	s_nop 3
	s_mul_i32 s101, s101, 5
	s_lshl_b32 s100, s100, 8
	s_add_i32 s100, s100, 0xbfa1400
	v_mov_b32_e32 v0, s100
	v_mov_b32_e32 v2, 1
	global_atomic_add v0, v2, s[86:87]

; DI unsigned xb_ld(unsigned* p) { return __hip_atomic_load(p, __ATOMIC_RELAXED, __HIP_MEMORY_SCOPE_AGENT); }
; DI void xcd_barrier_complete(unsigned* bar, unsigned x, unsigned& nloc, unsigned& nx) {
;   const unsigned G = gridDim.x * gridDim.y * gridDim.z;
;   unsigned sum, cnt, mine, sp = 0u;
;   for (;;) {
;     sum = 0u; cnt = 0u; mine = 0u;
; #pragma unroll
;     for (unsigned j = 0; j < 16; ++j) { const unsigned c = xb_ld(&bar[XB_XCNT(j)]); sum += c; cnt += (c > 0u) ? 1u : 0u; mine = (j == x) ? c : mine; }
; DI void xcd_barrier(const XcdBarrier& b) {
;     ...
;   if (threadIdx.x == 0) {
;     unsigned* bar = b.bar;
;     __builtin_amdgcn_s_waitcnt(0);
;     unsigned nloc = b.st[0], nx = b.st[1];
;     if (nloc == 0u) { xcd_barrier_complete(bar, b.x, nloc, nx); b.st[0] = nloc; b.st[1] = nx; }
.Lfp_fb_5:
	v_mov_b32_e32 v0, 0
	s_waitcnt vmcnt(0) expcnt(0) lgkmcnt(0)
	ds_read_b32 v2, v0 offset:256
	ds_read_b32 v1, v0 offset:260
	s_waitcnt lgkmcnt(1)
	v_cmp_ne_u32_e32 vcc, 0, v2
	s_cbranch_vccnz .LBB0_670
	s_add_u32 s6, s86, 0xbfa0200
	s_addc_u32 s7, s87, 0
	s_add_u32 s8, s86, 0xbfa0400
	s_addc_u32 s9, s87, 0
	s_add_u32 s10, s86, 0xbfa0500
	s_addc_u32 s11, s87, 0
	s_add_u32 s12, s86, 0xbfa0600
	s_addc_u32 s13, s87, 0
	s_add_u32 s14, s86, 0xbfa0700
	s_addc_u32 s15, s87, 0
	s_add_u32 s20, s86, 0xbfa0800
	s_addc_u32 s21, s87, 0
	s_add_u32 s22, s86, 0xbfa0900
	s_addc_u32 s23, s87, 0
	s_add_u32 s24, s86, 0xbfa0a00
	s_addc_u32 s25, s87, 0
	s_add_u32 s26, s86, 0xbfa0b00
	s_addc_u32 s27, s87, 0
	s_add_u32 s28, s86, 0xbfa0c00
	s_addc_u32 s29, s87, 0
	s_add_u32 s30, s86, 0xbfa0d00
	s_addc_u32 s31, s87, 0
	s_add_u32 s34, s86, 0xbfa0e00
	s_addc_u32 s35, s87, 0
	s_add_u32 s36, s86, 0xbfa0f00
	s_addc_u32 s37, s87, 0
	s_add_u32 s38, s86, 0xbfa1000
	s_addc_u32 s39, s87, 0
	s_add_u32 s40, s86, 0xbfa1100
	s_addc_u32 s41, s87, 0
	s_add_u32 s44, s86, 0xbfa1200
	v_readlane_b32 s2, v254, 4
	s_addc_u32 s45, s87, 0
	s_mul_i32 s2, s89, s2
	s_add_u32 s66, s86, 0xbfa1300
	s_mul_i32 s2, s2, s88
	s_addc_u32 s67, s87, 0
	s_mov_b32 s3, 1
	s_branch .LBB0_658

; DI unsigned xb_ld(unsigned* p) { return __hip_atomic_load(p, __ATOMIC_RELAXED, __HIP_MEMORY_SCOPE_AGENT); }
; DI unsigned xb_add(unsigned* p, unsigned v) { return __hip_atomic_fetch_add(p, v, __ATOMIC_RELAXED, __HIP_MEMORY_SCOPE_AGENT); }
; #define XB_SPIN(cond, bar) do { unsigned _sp = 0; while (cond) { __builtin_amdgcn_s_sleep(1); \
;     if ((++_sp & 255u) == 0u) { if (xb_ld(&(bar)[XB_TMO])) break; if (_sp > XB_SPIN_CAP) { atomicAdd(&(bar)[XB_TMO], 1u); break; } } } } while (0)
; DI void xcd_barrier(const XcdBarrier& b) {
;   asm volatile("s_waitcnt vmcnt(0)" ::: "memory");
;   __syncthreads();
;   if (threadIdx.x == 0) {
;     unsigned* bar = b.bar;
;     __builtin_amdgcn_s_waitcnt(0);
;     unsigned nloc = b.st[0], nx = b.st[1];
;     if (nloc == 0u) { xcd_barrier_complete(bar, b.x, nloc, nx); b.st[0] = nloc; b.st[1] = nx; }
;     const unsigned old = xb_add(&bar[XB_XSUB(b.x)], 1u);
;     const unsigned gen = old / nloc;
;     if (old + 1u == (gen + 1u) * nloc) {
;       __builtin_amdgcn_fence(__ATOMIC_RELEASE, "agent");
;       asm volatile("s_waitcnt vmcnt(0)" ::: "memory");
;       const unsigned og = xb_add(&bar[XB_TOP], 1u);
;       const unsigned tg = og / nx;
;       if (og + 1u == (tg + 1u) * nx) xb_add(&bar[XB_TOPGEN], 1u);
;       else XB_SPIN(xb_ld(&bar[XB_TOPGEN]) == tg, bar);
;       __builtin_amdgcn_fence(__ATOMIC_ACQUIRE, "agent");
;       xb_add(&bar[XB_XGEN(b.x)], 1u);
;       asm volatile("s_waitcnt vmcnt(0)" ::: "memory");
;     } else {
;       XB_SPIN(xb_ld(&bar[XB_XGEN(b.x)]) == gen, bar);
;       __builtin_amdgcn_fence(__ATOMIC_ACQUIRE, "agent");
;       asm volatile("s_waitcnt vmcnt(0)" ::: "memory");
;     }
;   }
;   __syncthreads();
; }
.LBB0_744:
	s_waitcnt vmcnt(0)
	s_waitcnt lgkmcnt(0)
	s_barrier
	s_and_saveexec_b64 s[0:1], s[94:95]
	s_cbranch_execz .LBB0_796
	v_mov_b32_e32 v0, 0
	ds_read_b32 v2, v0 offset:264
	s_waitcnt lgkmcnt(0)
	v_readfirstlane_b32 s100, v2
	s_nop 3
	s_cmp_lg_u32 s100, 0
	s_cbranch_scc0 .Lfp_fb_6
	buffer_inv sc1
	ds_read_b32 v2, v0 offset:256
	v_readlane_b32 s100, v254, 5
	s_waitcnt lgkmcnt(0)
	v_readfirstlane_b32 s101, v2
	s_nop 3
	s_mul_i32 s101, s101, 6
	s_lshl_b32 s100, s100, 8
	s_add_i32 s100, s100, 0xbfa1400
	v_mov_b32_e32 v0, s100
	v_mov_b32_e32 v2, 1
	global_atomic_add v0, v2, s[86:87]

; DI unsigned xb_ld(unsigned* p) { return __hip_atomic_load(p, __ATOMIC_RELAXED, __HIP_MEMORY_SCOPE_AGENT); }
; DI unsigned xb_add(unsigned* p, unsigned v) { return __hip_atomic_fetch_add(p, v, __ATOMIC_RELAXED, __HIP_MEMORY_SCOPE_AGENT); }
; #define XB_SPIN(cond, bar) do { unsigned _sp = 0; while (cond) { __builtin_amdgcn_s_sleep(1); \
;     if ((++_sp & 255u) == 0u) { if (xb_ld(&(bar)[XB_TMO])) break; if (_sp > XB_SPIN_CAP) { atomicAdd(&(bar)[XB_TMO], 1u); break; } } } } while (0)
; DI void xcd_barrier(const XcdBarrier& b) {
;     ...
;     if (old + 1u == (gen + 1u) * nloc) {
;       __builtin_amdgcn_fence(__ATOMIC_RELEASE, "agent");
;       asm volatile("s_waitcnt vmcnt(0)" ::: "memory");
;       const unsigned og = xb_add(&bar[XB_TOP], 1u);
;       const unsigned tg = og / nx;
;       if (og + 1u == (tg + 1u) * nx) xb_add(&bar[XB_TOPGEN], 1u);
;       else XB_SPIN(xb_ld(&bar[XB_TOPGEN]) == tg, bar);
;       __builtin_amdgcn_fence(__ATOMIC_ACQUIRE, "agent");
.Lfp_done_6:
	v_readlane_b32 s100, v254, 20
	s_nop 3
	s_cmp_lt_u32 s100, 8
	s_cbranch_scc0 .Lfp_na_6
	v_mov_b32_e32 v0, 0xbfa0210
	v_mov_b32_e32 v2, 1
	global_atomic_add v0, v2, s[86:87]
	s_waitcnt vmcnt(0)

; DI unsigned xb_ld(unsigned* p) { return __hip_atomic_load(p, __ATOMIC_RELAXED, __HIP_MEMORY_SCOPE_AGENT); }
; DI unsigned xb_add(unsigned* p, unsigned v) { return __hip_atomic_fetch_add(p, v, __ATOMIC_RELAXED, __HIP_MEMORY_SCOPE_AGENT); }
; #define XB_SPIN(cond, bar) do { unsigned _sp = 0; while (cond) { __builtin_amdgcn_s_sleep(1); \
;     if ((++_sp & 255u) == 0u) { if (xb_ld(&(bar)[XB_TMO])) break; if (_sp > XB_SPIN_CAP) { atomicAdd(&(bar)[XB_TMO], 1u); break; } } } } while (0)
; DI void xcd_barrier(const XcdBarrier& b) {
;   asm volatile("s_waitcnt vmcnt(0)" ::: "memory");
;   __syncthreads();
;   if (threadIdx.x == 0) {
;     unsigned* bar = b.bar;
;     __builtin_amdgcn_s_waitcnt(0);
;     unsigned nloc = b.st[0], nx = b.st[1];
;     if (nloc == 0u) { xcd_barrier_complete(bar, b.x, nloc, nx); b.st[0] = nloc; b.st[1] = nx; }
;     const unsigned old = xb_add(&bar[XB_XSUB(b.x)], 1u);
;     const unsigned gen = old / nloc;
;     if (old + 1u == (gen + 1u) * nloc) {
;       __builtin_amdgcn_fence(__ATOMIC_RELEASE, "agent");
;       asm volatile("s_waitcnt vmcnt(0)" ::: "memory");
;       const unsigned og = xb_add(&bar[XB_TOP], 1u);
;       const unsigned tg = og / nx;
;       if (og + 1u == (tg + 1u) * nx) xb_add(&bar[XB_TOPGEN], 1u);
;       else XB_SPIN(xb_ld(&bar[XB_TOPGEN]) == tg, bar);
;       __builtin_amdgcn_fence(__ATOMIC_ACQUIRE, "agent");
;       xb_add(&bar[XB_XGEN(b.x)], 1u);
;       asm volatile("s_waitcnt vmcnt(0)" ::: "memory");
;     } else {
;       XB_SPIN(xb_ld(&bar[XB_XGEN(b.x)]) == gen, bar);
;       __builtin_amdgcn_fence(__ATOMIC_ACQUIRE, "agent");
;       asm volatile("s_waitcnt vmcnt(0)" ::: "memory");
;     }
;   }
;   __syncthreads();
; }
.LBB0_862:
	s_waitcnt vmcnt(0)
	s_waitcnt lgkmcnt(0)
	s_barrier
	s_and_saveexec_b64 s[0:1], s[94:95]
	s_cbranch_execz .LBB0_915
	v_mov_b32_e32 v0, 0
	ds_read_b32 v2, v0 offset:264
	s_waitcnt lgkmcnt(0)
	v_readfirstlane_b32 s100, v2
	s_nop 3
	s_cmp_lg_u32 s100, 0
	s_cbranch_scc0 .Lfp_fb_7
	buffer_inv sc1
	ds_read_b32 v2, v0 offset:256
	v_readlane_b32 s100, v254, 5
	s_waitcnt lgkmcnt(0)
	v_readfirstlane_b32 s101, v2
	s_nop 3
	s_mul_i32 s101, s101, 7
	s_lshl_b32 s100, s100, 8
	s_add_i32 s100, s100, 0xbfa1400
	v_mov_b32_e32 v0, s100
	v_mov_b32_e32 v2, 1
	global_atomic_add v0, v2, s[86:87]

; DI unsigned xb_ld(unsigned* p) { return __hip_atomic_load(p, __ATOMIC_RELAXED, __HIP_MEMORY_SCOPE_AGENT); }
; DI unsigned xb_add(unsigned* p, unsigned v) { return __hip_atomic_fetch_add(p, v, __ATOMIC_RELAXED, __HIP_MEMORY_SCOPE_AGENT); }
; #define XB_SPIN(cond, bar) do { unsigned _sp = 0; while (cond) { __builtin_amdgcn_s_sleep(1); \
;     if ((++_sp & 255u) == 0u) { if (xb_ld(&(bar)[XB_TMO])) break; if (_sp > XB_SPIN_CAP) { atomicAdd(&(bar)[XB_TMO], 1u); break; } } } } while (0)
; DI void xcd_barrier(const XcdBarrier& b) {
;     ...
;     if (old + 1u == (gen + 1u) * nloc) {
;       __builtin_amdgcn_fence(__ATOMIC_RELEASE, "agent");
;       asm volatile("s_waitcnt vmcnt(0)" ::: "memory");
;       const unsigned og = xb_add(&bar[XB_TOP], 1u);
;       const unsigned tg = og / nx;
;       if (og + 1u == (tg + 1u) * nx) xb_add(&bar[XB_TOPGEN], 1u);
;       else XB_SPIN(xb_ld(&bar[XB_TOPGEN]) == tg, bar);
;       __builtin_amdgcn_fence(__ATOMIC_ACQUIRE, "agent");
.Lfp_done_7:
	s_min_u32 s101, s88, 8
	v_mov_b32_e32 v0, 0xbfa0210

; DI unsigned xb_ld(unsigned* p) { return __hip_atomic_load(p, __ATOMIC_RELAXED, __HIP_MEMORY_SCOPE_AGENT); }
; DI void xcd_barrier_complete(unsigned* bar, unsigned x, unsigned& nloc, unsigned& nx) {
;   const unsigned G = gridDim.x * gridDim.y * gridDim.z;
;   unsigned sum, cnt, mine, sp = 0u;
;   for (;;) {
;     sum = 0u; cnt = 0u; mine = 0u;
; #pragma unroll
;     for (unsigned j = 0; j < 16; ++j) { const unsigned c = xb_ld(&bar[XB_XCNT(j)]); sum += c; cnt += (c > 0u) ? 1u : 0u; mine = (j == x) ? c : mine; }
; DI void xcd_barrier(const XcdBarrier& b) {
;     ...
;   if (threadIdx.x == 0) {
;     unsigned* bar = b.bar;
;     __builtin_amdgcn_s_waitcnt(0);
;     unsigned nloc = b.st[0], nx = b.st[1];
;     if (nloc == 0u) { xcd_barrier_complete(bar, b.x, nloc, nx); b.st[0] = nloc; b.st[1] = nx; }
.Lfp_fb_7:
	v_mov_b32_e32 v0, 0
	s_waitcnt vmcnt(0) expcnt(0) lgkmcnt(0)
	ds_read_b32 v2, v0 offset:256
	ds_read_b32 v1, v0 offset:260
	s_waitcnt lgkmcnt(1)
	v_cmp_ne_u32_e32 vcc, 0, v2
	s_cbranch_vccnz .LBB0_879
	s_add_u32 s6, s86, 0xbfa0200
	s_addc_u32 s7, s87, 0
	s_add_u32 s8, s86, 0xbfa0400
	s_addc_u32 s9, s87, 0
	s_add_u32 s10, s86, 0xbfa0500
	s_addc_u32 s11, s87, 0
	s_add_u32 s12, s86, 0xbfa0600
	s_addc_u32 s13, s87, 0
	s_add_u32 s14, s86, 0xbfa0700
	s_addc_u32 s15, s87, 0
	s_add_u32 s20, s86, 0xbfa0800
	s_addc_u32 s21, s87, 0
	s_add_u32 s22, s86, 0xbfa0900
	s_addc_u32 s23, s87, 0
	s_add_u32 s26, s86, 0xbfa0a00
	s_addc_u32 s27, s87, 0
	s_add_u32 s28, s86, 0xbfa0b00
	s_addc_u32 s29, s87, 0
	s_add_u32 s30, s86, 0xbfa0c00
	s_addc_u32 s31, s87, 0
	s_add_u32 s34, s86, 0xbfa0d00
	s_addc_u32 s35, s87, 0
	s_add_u32 s36, s86, 0xbfa0e00
	s_addc_u32 s37, s87, 0
	s_add_u32 s38, s86, 0xbfa0f00
	s_addc_u32 s39, s87, 0
	s_add_u32 s40, s86, 0xbfa1000
	s_addc_u32 s41, s87, 0
	s_add_u32 s44, s86, 0xbfa1100
	s_addc_u32 s45, s87, 0
	s_add_u32 s66, s86, 0xbfa1200
	v_readlane_b32 s2, v254, 4
	s_addc_u32 s67, s87, 0
	s_mul_i32 s2, s89, s2
	s_add_u32 s70, s86, 0xbfa1300
	s_mul_i32 s2, s2, s88
	s_addc_u32 s71, s87, 0
	s_mov_b32 s3, 1
	s_branch .LBB0_867

; DI unsigned xb_ld(unsigned* p) { return __hip_atomic_load(p, __ATOMIC_RELAXED, __HIP_MEMORY_SCOPE_AGENT); }
; DI unsigned xb_add(unsigned* p, unsigned v) { return __hip_atomic_fetch_add(p, v, __ATOMIC_RELAXED, __HIP_MEMORY_SCOPE_AGENT); }
; #define XB_SPIN(cond, bar) do { unsigned _sp = 0; while (cond) { __builtin_amdgcn_s_sleep(1); \
;     if ((++_sp & 255u) == 0u) { if (xb_ld(&(bar)[XB_TMO])) break; if (_sp > XB_SPIN_CAP) { atomicAdd(&(bar)[XB_TMO], 1u); break; } } } } while (0)
; DI void xcd_barrier(const XcdBarrier& b) {
;   asm volatile("s_waitcnt vmcnt(0)" ::: "memory");
;   __syncthreads();
;   if (threadIdx.x == 0) {
;     unsigned* bar = b.bar;
;     __builtin_amdgcn_s_waitcnt(0);
;     unsigned nloc = b.st[0], nx = b.st[1];
;     if (nloc == 0u) { xcd_barrier_complete(bar, b.x, nloc, nx); b.st[0] = nloc; b.st[1] = nx; }
;     const unsigned old = xb_add(&bar[XB_XSUB(b.x)], 1u);
;     const unsigned gen = old / nloc;
;     if (old + 1u == (gen + 1u) * nloc) {
;       __builtin_amdgcn_fence(__ATOMIC_RELEASE, "agent");
;       asm volatile("s_waitcnt vmcnt(0)" ::: "memory");
;       const unsigned og = xb_add(&bar[XB_TOP], 1u);
;       const unsigned tg = og / nx;
;       if (og + 1u == (tg + 1u) * nx) xb_add(&bar[XB_TOPGEN], 1u);
;       else XB_SPIN(xb_ld(&bar[XB_TOPGEN]) == tg, bar);
;       __builtin_amdgcn_fence(__ATOMIC_ACQUIRE, "agent");
;       xb_add(&bar[XB_XGEN(b.x)], 1u);
;       asm volatile("s_waitcnt vmcnt(0)" ::: "memory");
;     } else {
;       XB_SPIN(xb_ld(&bar[XB_XGEN(b.x)]) == gen, bar);
;       __builtin_amdgcn_fence(__ATOMIC_ACQUIRE, "agent");
;       asm volatile("s_waitcnt vmcnt(0)" ::: "memory");
;     }
;   }
;   __syncthreads();
; }
.LBB0_1057:
	s_waitcnt vmcnt(0)
	s_barrier
	s_and_saveexec_b64 s[0:1], s[94:95]
	s_cbranch_execz .LBB0_1109
	v_mov_b32_e32 v0, 0
	ds_read_b32 v2, v0 offset:264
	s_waitcnt lgkmcnt(0)
	v_readfirstlane_b32 s100, v2
	s_nop 3
	s_cmp_lg_u32 s100, 0
	s_cbranch_scc0 .Lfp_fb_8
	buffer_inv sc1
	ds_read_b32 v2, v0 offset:256
	v_readlane_b32 s100, v254, 5
	s_waitcnt lgkmcnt(0)
	v_readfirstlane_b32 s101, v2
	s_nop 3
	s_mul_i32 s101, s101, 8
	s_lshl_b32 s100, s100, 8
	s_add_i32 s100, s100, 0xbfa1400
	v_mov_b32_e32 v0, s100
	v_mov_b32_e32 v2, 1
	global_atomic_add v0, v2, s[86:87]

; DI unsigned xb_ld(unsigned* p) { return __hip_atomic_load(p, __ATOMIC_RELAXED, __HIP_MEMORY_SCOPE_AGENT); }
; DI void xcd_barrier_complete(unsigned* bar, unsigned x, unsigned& nloc, unsigned& nx) {
;   const unsigned G = gridDim.x * gridDim.y * gridDim.z;
;   unsigned sum, cnt, mine, sp = 0u;
;   for (;;) {
;     sum = 0u; cnt = 0u; mine = 0u;
; #pragma unroll
;     for (unsigned j = 0; j < 16; ++j) { const unsigned c = xb_ld(&bar[XB_XCNT(j)]); sum += c; cnt += (c > 0u) ? 1u : 0u; mine = (j == x) ? c : mine; }
; DI void xcd_barrier(const XcdBarrier& b) {
;     ...
;   if (threadIdx.x == 0) {
;     unsigned* bar = b.bar;
;     __builtin_amdgcn_s_waitcnt(0);
;     unsigned nloc = b.st[0], nx = b.st[1];
;     if (nloc == 0u) { xcd_barrier_complete(bar, b.x, nloc, nx); b.st[0] = nloc; b.st[1] = nx; }
.Lfp_fb_8:
	v_mov_b32_e32 v0, 0
	s_waitcnt vmcnt(0) expcnt(0) lgkmcnt(0)
	ds_read_b32 v2, v0 offset:256
	ds_read_b32 v1, v0 offset:260
	s_waitcnt lgkmcnt(1)
	v_cmp_ne_u32_e32 vcc, 0, v2
	s_cbranch_vccnz .LBB0_1073
	s_add_u32 s6, s86, 0xbfa0200
	s_addc_u32 s7, s87, 0
	s_add_u32 s8, s86, 0xbfa0400
	s_addc_u32 s9, s87, 0
	s_add_u32 s10, s86, 0xbfa0500
	s_addc_u32 s11, s87, 0
	s_add_u32 s12, s86, 0xbfa0600
	s_addc_u32 s13, s87, 0
	s_add_u32 s24, s86, 0xbfa0700
	s_addc_u32 s25, s87, 0
	s_add_u32 s26, s86, 0xbfa0800
	s_addc_u32 s27, s87, 0
	s_add_u32 s28, s86, 0xbfa0900
	s_addc_u32 s29, s87, 0
	s_add_u32 s30, s86, 0xbfa0a00
	s_addc_u32 s31, s87, 0
	s_add_u32 s34, s86, 0xbfa0b00
	s_addc_u32 s35, s87, 0
	s_add_u32 s36, s86, 0xbfa0c00
	s_addc_u32 s37, s87, 0
	s_add_u32 s38, s86, 0xbfa0d00
	s_addc_u32 s39, s87, 0
	s_add_u32 s40, s86, 0xbfa0e00
	s_addc_u32 s41, s87, 0
	s_add_u32 s44, s86, 0xbfa0f00
	s_addc_u32 s45, s87, 0
	s_add_u32 s62, s86, 0xbfa1000
	s_addc_u32 s63, s87, 0
	s_add_u32 s64, s86, 0xbfa1100
	s_addc_u32 s65, s87, 0
	s_add_u32 s66, s86, 0xbfa1200
	v_readlane_b32 s2, v254, 4
	s_addc_u32 s67, s87, 0
	s_mul_i32 s2, s89, s2
	s_add_u32 s70, s86, 0xbfa1300
	s_mul_i32 s2, s2, s88
	s_addc_u32 s71, s87, 0
	s_mov_b32 s3, 1
	s_branch .LBB0_1061

; DI unsigned xb_ld(unsigned* p) { return __hip_atomic_load(p, __ATOMIC_RELAXED, __HIP_MEMORY_SCOPE_AGENT); }
; DI unsigned xb_add(unsigned* p, unsigned v) { return __hip_atomic_fetch_add(p, v, __ATOMIC_RELAXED, __HIP_MEMORY_SCOPE_AGENT); }
; #define XB_SPIN(cond, bar) do { unsigned _sp = 0; while (cond) { __builtin_amdgcn_s_sleep(1); \
;     if ((++_sp & 255u) == 0u) { if (xb_ld(&(bar)[XB_TMO])) break; if (_sp > XB_SPIN_CAP) { atomicAdd(&(bar)[XB_TMO], 1u); break; } } } } while (0)
; DI void xcd_barrier(const XcdBarrier& b) {
;   asm volatile("s_waitcnt vmcnt(0)" ::: "memory");
;   __syncthreads();
;   if (threadIdx.x == 0) {
;     unsigned* bar = b.bar;
;     __builtin_amdgcn_s_waitcnt(0);
;     unsigned nloc = b.st[0], nx = b.st[1];
;     if (nloc == 0u) { xcd_barrier_complete(bar, b.x, nloc, nx); b.st[0] = nloc; b.st[1] = nx; }
;     const unsigned old = xb_add(&bar[XB_XSUB(b.x)], 1u);
;     const unsigned gen = old / nloc;
;     if (old + 1u == (gen + 1u) * nloc) {
;       __builtin_amdgcn_fence(__ATOMIC_RELEASE, "agent");
;       asm volatile("s_waitcnt vmcnt(0)" ::: "memory");
;       const unsigned og = xb_add(&bar[XB_TOP], 1u);
;       const unsigned tg = og / nx;
;       if (og + 1u == (tg + 1u) * nx) xb_add(&bar[XB_TOPGEN], 1u);
;       else XB_SPIN(xb_ld(&bar[XB_TOPGEN]) == tg, bar);
;       __builtin_amdgcn_fence(__ATOMIC_ACQUIRE, "agent");
;       xb_add(&bar[XB_XGEN(b.x)], 1u);
;       asm volatile("s_waitcnt vmcnt(0)" ::: "memory");
;     } else {
;       XB_SPIN(xb_ld(&bar[XB_XGEN(b.x)]) == gen, bar);
;       __builtin_amdgcn_fence(__ATOMIC_ACQUIRE, "agent");
;       asm volatile("s_waitcnt vmcnt(0)" ::: "memory");
;     }
;   }
;   __syncthreads();
; }
.Lhp_done:
.LBB0_1112:
	s_or_b64 exec, exec, s[6:7]
	s_waitcnt vmcnt(0)
	s_barrier
	s_and_saveexec_b64 s[0:1], s[94:95]
	s_cbranch_execz .LBB0_1164
	v_mov_b32_e32 v0, 0
	ds_read_b32 v2, v0 offset:264
	s_waitcnt lgkmcnt(0)
	v_readfirstlane_b32 s100, v2
	s_nop 3
	s_cmp_lg_u32 s100, 0
	s_cbranch_scc0 .Lfp_fb_9
	buffer_inv sc1
	ds_read_b32 v2, v0 offset:256
	v_readlane_b32 s100, v254, 5
	s_waitcnt lgkmcnt(0)
	v_readfirstlane_b32 s101, v2
	s_nop 3
	s_mul_i32 s101, s101, 9
	s_lshl_b32 s100, s100, 8
	s_add_i32 s100, s100, 0xbfa1400
	v_mov_b32_e32 v0, s100
	v_mov_b32_e32 v2, 1
	global_atomic_add v0, v2, s[86:87]

; DI unsigned xb_ld(unsigned* p) { return __hip_atomic_load(p, __ATOMIC_RELAXED, __HIP_MEMORY_SCOPE_AGENT); }
; DI void xcd_barrier_complete(unsigned* bar, unsigned x, unsigned& nloc, unsigned& nx) {
;   const unsigned G = gridDim.x * gridDim.y * gridDim.z;
;   unsigned sum, cnt, mine, sp = 0u;
;   for (;;) {
;     sum = 0u; cnt = 0u; mine = 0u;
; #pragma unroll
;     for (unsigned j = 0; j < 16; ++j) { const unsigned c = xb_ld(&bar[XB_XCNT(j)]); sum += c; cnt += (c > 0u) ? 1u : 0u; mine = (j == x) ? c : mine; }
; DI void xcd_barrier(const XcdBarrier& b) {
;     ...
;   if (threadIdx.x == 0) {
;     unsigned* bar = b.bar;
;     __builtin_amdgcn_s_waitcnt(0);
;     unsigned nloc = b.st[0], nx = b.st[1];
;     if (nloc == 0u) { xcd_barrier_complete(bar, b.x, nloc, nx); b.st[0] = nloc; b.st[1] = nx; }
.Lfp_fb_9:
	v_mov_b32_e32 v0, 0
	s_waitcnt vmcnt(0) expcnt(0) lgkmcnt(0)
	ds_read_b32 v2, v0 offset:256
	ds_read_b32 v1, v0 offset:260
	s_waitcnt lgkmcnt(1)
	v_cmp_ne_u32_e32 vcc, 0, v2
	s_cbranch_vccnz .LBB0_1128
	v_readlane_b32 s2, v254, 4
	s_mul_i32 s4, s89, s2
	s_add_u32 s2, s86, 0xbfa0200
	s_addc_u32 s3, s87, 0
	s_add_u32 s6, s86, 0xbfa0400
	s_addc_u32 s7, s87, 0
	s_add_u32 s8, s86, 0xbfa0500
	s_addc_u32 s9, s87, 0
	s_add_u32 s10, s86, 0xbfa0600
	s_addc_u32 s11, s87, 0
	s_add_u32 s12, s86, 0xbfa0700
	s_addc_u32 s13, s87, 0
	s_add_u32 s24, s86, 0xbfa0800
	s_addc_u32 s25, s87, 0
	s_add_u32 s26, s86, 0xbfa0900
	s_addc_u32 s27, s87, 0
	s_add_u32 s28, s86, 0xbfa0a00
	s_addc_u32 s29, s87, 0
	s_add_u32 s30, s86, 0xbfa0b00
	s_addc_u32 s31, s87, 0
	s_add_u32 s34, s86, 0xbfa0c00
	s_addc_u32 s35, s87, 0
	s_add_u32 s36, s86, 0xbfa0d00
	s_addc_u32 s37, s87, 0
	s_add_u32 s38, s86, 0xbfa0e00
	s_addc_u32 s39, s87, 0
	s_add_u32 s40, s86, 0xbfa0f00
	s_addc_u32 s41, s87, 0
	s_add_u32 s44, s86, 0xbfa1000
	s_addc_u32 s45, s87, 0
	s_add_u32 s62, s86, 0xbfa1100
	s_addc_u32 s63, s87, 0
	s_add_u32 s64, s86, 0xbfa1200
	s_addc_u32 s65, s87, 0
	s_add_u32 s66, s86, 0xbfa1300
	s_mul_i32 s4, s4, s88
	s_addc_u32 s67, s87, 0
	s_mov_b32 s5, 1
	s_branch .LBB0_1116

; DI unsigned xb_ld(unsigned* p) { return __hip_atomic_load(p, __ATOMIC_RELAXED, __HIP_MEMORY_SCOPE_AGENT); }
; DI unsigned xb_add(unsigned* p, unsigned v) { return __hip_atomic_fetch_add(p, v, __ATOMIC_RELAXED, __HIP_MEMORY_SCOPE_AGENT); }
; #define XB_SPIN(cond, bar) do { unsigned _sp = 0; while (cond) { __builtin_amdgcn_s_sleep(1); \
;     if ((++_sp & 255u) == 0u) { if (xb_ld(&(bar)[XB_TMO])) break; if (_sp > XB_SPIN_CAP) { atomicAdd(&(bar)[XB_TMO], 1u); break; } } } } while (0)
; DI void xcd_barrier(const XcdBarrier& b) {
;   asm volatile("s_waitcnt vmcnt(0)" ::: "memory");
;   __syncthreads();
;   if (threadIdx.x == 0) {
;     unsigned* bar = b.bar;
;     __builtin_amdgcn_s_waitcnt(0);
;     unsigned nloc = b.st[0], nx = b.st[1];
;     if (nloc == 0u) { xcd_barrier_complete(bar, b.x, nloc, nx); b.st[0] = nloc; b.st[1] = nx; }
;     const unsigned old = xb_add(&bar[XB_XSUB(b.x)], 1u);
;     const unsigned gen = old / nloc;
;     if (old + 1u == (gen + 1u) * nloc) {
;       __builtin_amdgcn_fence(__ATOMIC_RELEASE, "agent");
;       asm volatile("s_waitcnt vmcnt(0)" ::: "memory");
;       const unsigned og = xb_add(&bar[XB_TOP], 1u);
;       const unsigned tg = og / nx;
;       if (og + 1u == (tg + 1u) * nx) xb_add(&bar[XB_TOPGEN], 1u);
;       else XB_SPIN(xb_ld(&bar[XB_TOPGEN]) == tg, bar);
;       __builtin_amdgcn_fence(__ATOMIC_ACQUIRE, "agent");
;       xb_add(&bar[XB_XGEN(b.x)], 1u);
;       asm volatile("s_waitcnt vmcnt(0)" ::: "memory");
;     } else {
;       XB_SPIN(xb_ld(&bar[XB_XGEN(b.x)]) == gen, bar);
;       __builtin_amdgcn_fence(__ATOMIC_ACQUIRE, "agent");
;       asm volatile("s_waitcnt vmcnt(0)" ::: "memory");
;     }
;   }
;   __syncthreads();
; }
.LBB0_1237:
	s_waitcnt vmcnt(0)
	s_barrier
	s_and_saveexec_b64 s[0:1], s[94:95]
	s_cbranch_execz .LBB0_1289
	v_mov_b32_e32 v0, 0
	ds_read_b32 v2, v0 offset:264
	s_waitcnt lgkmcnt(0)
	v_readfirstlane_b32 s100, v2
	s_nop 3
	s_cmp_lg_u32 s100, 0
	s_cbranch_scc0 .Lfp_fb_10
	buffer_inv sc1
	ds_read_b32 v2, v0 offset:256
	v_readlane_b32 s100, v254, 5
	s_waitcnt lgkmcnt(0)
	v_readfirstlane_b32 s101, v2
	s_nop 3
	s_mul_i32 s101, s101, 10
	s_lshl_b32 s100, s100, 8
	s_add_i32 s100, s100, 0xbfa1400
	v_mov_b32_e32 v0, s100
	v_mov_b32_e32 v2, 1
	global_atomic_add v0, v2, s[86:87]

; DI unsigned xb_ld(unsigned* p) { return __hip_atomic_load(p, __ATOMIC_RELAXED, __HIP_MEMORY_SCOPE_AGENT); }
; DI unsigned xb_add(unsigned* p, unsigned v) { return __hip_atomic_fetch_add(p, v, __ATOMIC_RELAXED, __HIP_MEMORY_SCOPE_AGENT); }
; #define XB_SPIN(cond, bar) do { unsigned _sp = 0; while (cond) { __builtin_amdgcn_s_sleep(1); \
;     if ((++_sp & 255u) == 0u) { if (xb_ld(&(bar)[XB_TMO])) break; if (_sp > XB_SPIN_CAP) { atomicAdd(&(bar)[XB_TMO], 1u); break; } } } } while (0)
; DI void xcd_barrier(const XcdBarrier& b) {
;     ...
;     if (old + 1u == (gen + 1u) * nloc) {
;       __builtin_amdgcn_fence(__ATOMIC_RELEASE, "agent");
;       asm volatile("s_waitcnt vmcnt(0)" ::: "memory");
;       const unsigned og = xb_add(&bar[XB_TOP], 1u);
;       const unsigned tg = og / nx;
;       if (og + 1u == (tg + 1u) * nx) xb_add(&bar[XB_TOPGEN], 1u);
;       else XB_SPIN(xb_ld(&bar[XB_TOPGEN]) == tg, bar);
;       __builtin_amdgcn_fence(__ATOMIC_ACQUIRE, "agent");
.Lfp_done_10:
	v_readlane_b32 s100, v254, 20
	s_nop 3
	s_cmp_lt_u32 s100, 8
	s_cbranch_scc0 .Lfp_na_10
	v_mov_b32_e32 v0, 0xbfa020c
	v_mov_b32_e32 v2, 1
	global_atomic_add v0, v2, s[86:87]
	s_waitcnt vmcnt(0)

; DI unsigned xb_ld(unsigned* p) { return __hip_atomic_load(p, __ATOMIC_RELAXED, __HIP_MEMORY_SCOPE_AGENT); }
; DI void xcd_barrier_complete(unsigned* bar, unsigned x, unsigned& nloc, unsigned& nx) {
;   const unsigned G = gridDim.x * gridDim.y * gridDim.z;
;   unsigned sum, cnt, mine, sp = 0u;
;   for (;;) {
;     sum = 0u; cnt = 0u; mine = 0u;
; #pragma unroll
;     for (unsigned j = 0; j < 16; ++j) { const unsigned c = xb_ld(&bar[XB_XCNT(j)]); sum += c; cnt += (c > 0u) ? 1u : 0u; mine = (j == x) ? c : mine; }
; DI void xcd_barrier(const XcdBarrier& b) {
;     ...
;   if (threadIdx.x == 0) {
;     unsigned* bar = b.bar;
;     __builtin_amdgcn_s_waitcnt(0);
;     unsigned nloc = b.st[0], nx = b.st[1];
;     if (nloc == 0u) { xcd_barrier_complete(bar, b.x, nloc, nx); b.st[0] = nloc; b.st[1] = nx; }
.Lfp_fb_10:
	v_mov_b32_e32 v0, 0
	s_waitcnt vmcnt(0) expcnt(0) lgkmcnt(0)
	ds_read_b32 v2, v0 offset:256
	ds_read_b32 v1, v0 offset:260
	s_waitcnt lgkmcnt(1)
	v_cmp_ne_u32_e32 vcc, 0, v2
	s_cbranch_vccnz .LBB0_1253
	v_readlane_b32 s2, v254, 4
	s_mul_i32 s4, s89, s2
	s_add_u32 s2, s86, 0xbfa0200
	s_addc_u32 s3, s87, 0
	s_add_u32 s6, s86, 0xbfa0400
	s_addc_u32 s7, s87, 0
	s_add_u32 s8, s86, 0xbfa0500
	s_addc_u32 s9, s87, 0
	s_add_u32 s10, s86, 0xbfa0600
	s_addc_u32 s11, s87, 0
	s_add_u32 s12, s86, 0xbfa0700
	s_addc_u32 s13, s87, 0
	s_add_u32 s14, s86, 0xbfa0800
	s_addc_u32 s15, s87, 0
	s_add_u32 s20, s86, 0xbfa0900
	s_addc_u32 s21, s87, 0
	s_add_u32 s22, s86, 0xbfa0a00
	s_addc_u32 s23, s87, 0
	s_add_u32 s24, s86, 0xbfa0b00
	s_addc_u32 s25, s87, 0
	s_add_u32 s26, s86, 0xbfa0c00
	s_addc_u32 s27, s87, 0
	s_add_u32 s28, s86, 0xbfa0d00
	s_addc_u32 s29, s87, 0
	s_add_u32 s30, s86, 0xbfa0e00
	s_addc_u32 s31, s87, 0
	s_add_u32 s34, s86, 0xbfa0f00
	s_addc_u32 s35, s87, 0
	s_add_u32 s36, s86, 0xbfa1000
	s_addc_u32 s37, s87, 0
	s_add_u32 s38, s86, 0xbfa1100
	s_addc_u32 s39, s87, 0
	s_add_u32 s40, s86, 0xbfa1200
	s_addc_u32 s41, s87, 0
	s_add_u32 s44, s86, 0xbfa1300
	s_mul_i32 s4, s4, s88
	s_addc_u32 s45, s87, 0
	s_mov_b32 s5, 1
	s_branch .LBB0_1241

; DI unsigned xb_ld(unsigned* p) { return __hip_atomic_load(p, __ATOMIC_RELAXED, __HIP_MEMORY_SCOPE_AGENT); }
; DI unsigned xb_add(unsigned* p, unsigned v) { return __hip_atomic_fetch_add(p, v, __ATOMIC_RELAXED, __HIP_MEMORY_SCOPE_AGENT); }
; #define XB_SPIN(cond, bar) do { unsigned _sp = 0; while (cond) { __builtin_amdgcn_s_sleep(1); \
;     if ((++_sp & 255u) == 0u) { if (xb_ld(&(bar)[XB_TMO])) break; if (_sp > XB_SPIN_CAP) { atomicAdd(&(bar)[XB_TMO], 1u); break; } } } } while (0)
; DI void xcd_barrier(const XcdBarrier& b) {
;   asm volatile("s_waitcnt vmcnt(0)" ::: "memory");
;   __syncthreads();
;   if (threadIdx.x == 0) {
;     unsigned* bar = b.bar;
;     __builtin_amdgcn_s_waitcnt(0);
;     unsigned nloc = b.st[0], nx = b.st[1];
;     if (nloc == 0u) { xcd_barrier_complete(bar, b.x, nloc, nx); b.st[0] = nloc; b.st[1] = nx; }
;     const unsigned old = xb_add(&bar[XB_XSUB(b.x)], 1u);
;     const unsigned gen = old / nloc;
;     if (old + 1u == (gen + 1u) * nloc) {
;       __builtin_amdgcn_fence(__ATOMIC_RELEASE, "agent");
;       asm volatile("s_waitcnt vmcnt(0)" ::: "memory");
;       const unsigned og = xb_add(&bar[XB_TOP], 1u);
;       const unsigned tg = og / nx;
;       if (og + 1u == (tg + 1u) * nx) xb_add(&bar[XB_TOPGEN], 1u);
;       else XB_SPIN(xb_ld(&bar[XB_TOPGEN]) == tg, bar);
;       __builtin_amdgcn_fence(__ATOMIC_ACQUIRE, "agent");
;       xb_add(&bar[XB_XGEN(b.x)], 1u);
;       asm volatile("s_waitcnt vmcnt(0)" ::: "memory");
;     } else {
;       XB_SPIN(xb_ld(&bar[XB_XGEN(b.x)]) == gen, bar);
;       __builtin_amdgcn_fence(__ATOMIC_ACQUIRE, "agent");
;       asm volatile("s_waitcnt vmcnt(0)" ::: "memory");
;     }
;   }
;   __syncthreads();
; }
.LBB0_1323:
	s_waitcnt vmcnt(0)
	s_waitcnt lgkmcnt(0)
	s_barrier
	s_and_saveexec_b64 s[0:1], s[94:95]
	s_cbranch_execz .LBB0_1375
	v_mov_b32_e32 v0, 0
	ds_read_b32 v2, v0 offset:264
	s_waitcnt lgkmcnt(0)
	v_readfirstlane_b32 s100, v2
	s_nop 3
	s_cmp_lg_u32 s100, 0
	s_cbranch_scc0 .Lfp_fb_11
	buffer_inv sc1
	ds_read_b32 v2, v0 offset:256
	v_readlane_b32 s100, v254, 5
	s_waitcnt lgkmcnt(0)
	v_readfirstlane_b32 s101, v2
	s_nop 3
	s_mul_i32 s101, s101, 11
	s_lshl_b32 s100, s100, 8
	s_add_i32 s100, s100, 0xbfa1400
	v_mov_b32_e32 v0, s100
	v_mov_b32_e32 v2, 1
	global_atomic_add v0, v2, s[86:87]

; DI unsigned xb_ld(unsigned* p) { return __hip_atomic_load(p, __ATOMIC_RELAXED, __HIP_MEMORY_SCOPE_AGENT); }
; DI unsigned xb_add(unsigned* p, unsigned v) { return __hip_atomic_fetch_add(p, v, __ATOMIC_RELAXED, __HIP_MEMORY_SCOPE_AGENT); }
; #define XB_SPIN(cond, bar) do { unsigned _sp = 0; while (cond) { __builtin_amdgcn_s_sleep(1); \
;     if ((++_sp & 255u) == 0u) { if (xb_ld(&(bar)[XB_TMO])) break; if (_sp > XB_SPIN_CAP) { atomicAdd(&(bar)[XB_TMO], 1u); break; } } } } while (0)
; DI void xcd_barrier(const XcdBarrier& b) {
;     ...
;     if (old + 1u == (gen + 1u) * nloc) {
;       __builtin_amdgcn_fence(__ATOMIC_RELEASE, "agent");
;       asm volatile("s_waitcnt vmcnt(0)" ::: "memory");
;       const unsigned og = xb_add(&bar[XB_TOP], 1u);
;       const unsigned tg = og / nx;
;       if (og + 1u == (tg + 1u) * nx) xb_add(&bar[XB_TOPGEN], 1u);
;       else XB_SPIN(xb_ld(&bar[XB_TOPGEN]) == tg, bar);
;       __builtin_amdgcn_fence(__ATOMIC_ACQUIRE, "agent");
.Lfp_done_11:
	s_min_u32 s101, s88, 8
	v_mov_b32_e32 v0, 0xbfa020c

; DI unsigned xb_ld(unsigned* p) { return __hip_atomic_load(p, __ATOMIC_RELAXED, __HIP_MEMORY_SCOPE_AGENT); }
; DI unsigned xb_add(unsigned* p, unsigned v) { return __hip_atomic_fetch_add(p, v, __ATOMIC_RELAXED, __HIP_MEMORY_SCOPE_AGENT); }
; #define XB_SPIN(cond, bar) do { unsigned _sp = 0; while (cond) { __builtin_amdgcn_s_sleep(1); \
;     if ((++_sp & 255u) == 0u) { if (xb_ld(&(bar)[XB_TMO])) break; if (_sp > XB_SPIN_CAP) { atomicAdd(&(bar)[XB_TMO], 1u); break; } } } } while (0)
; DI void xcd_barrier(const XcdBarrier& b) {
;   asm volatile("s_waitcnt vmcnt(0)" ::: "memory");
;   __syncthreads();
;   if (threadIdx.x == 0) {
;     unsigned* bar = b.bar;
;     __builtin_amdgcn_s_waitcnt(0);
;     unsigned nloc = b.st[0], nx = b.st[1];
;     if (nloc == 0u) { xcd_barrier_complete(bar, b.x, nloc, nx); b.st[0] = nloc; b.st[1] = nx; }
;     const unsigned old = xb_add(&bar[XB_XSUB(b.x)], 1u);
;     const unsigned gen = old / nloc;
;     if (old + 1u == (gen + 1u) * nloc) {
;       __builtin_amdgcn_fence(__ATOMIC_RELEASE, "agent");
;       asm volatile("s_waitcnt vmcnt(0)" ::: "memory");
;       const unsigned og = xb_add(&bar[XB_TOP], 1u);
;       const unsigned tg = og / nx;
;       if (og + 1u == (tg + 1u) * nx) xb_add(&bar[XB_TOPGEN], 1u);
;       else XB_SPIN(xb_ld(&bar[XB_TOPGEN]) == tg, bar);
;       __builtin_amdgcn_fence(__ATOMIC_ACQUIRE, "agent");
;       xb_add(&bar[XB_XGEN(b.x)], 1u);
;       asm volatile("s_waitcnt vmcnt(0)" ::: "memory");
;     } else {
;       XB_SPIN(xb_ld(&bar[XB_XGEN(b.x)]) == gen, bar);
;       __builtin_amdgcn_fence(__ATOMIC_ACQUIRE, "agent");
;       asm volatile("s_waitcnt vmcnt(0)" ::: "memory");
;     }
;   }
;   __syncthreads();
; }
.LBB0_1391:
	s_waitcnt vmcnt(0)
	s_barrier
	s_and_saveexec_b64 s[0:1], s[94:95]
	s_cbranch_execz .LBB0_1443
	v_mov_b32_e32 v0, 0
	ds_read_b32 v2, v0 offset:264
	s_waitcnt lgkmcnt(0)
	v_readfirstlane_b32 s100, v2
	s_nop 3
	s_cmp_lg_u32 s100, 0
	s_cbranch_scc0 .Lfp_fb_12
	buffer_inv sc1
	ds_read_b32 v2, v0 offset:256
	v_readlane_b32 s100, v254, 5
	s_waitcnt lgkmcnt(0)
	v_readfirstlane_b32 s101, v2
	s_nop 3
	s_mul_i32 s101, s101, 12
	s_lshl_b32 s100, s100, 8
	s_add_i32 s100, s100, 0xbfa1400
	v_mov_b32_e32 v0, s100
	v_mov_b32_e32 v2, 1
	global_atomic_add v0, v2, s[86:87]

; DI unsigned xb_ld(unsigned* p) { return __hip_atomic_load(p, __ATOMIC_RELAXED, __HIP_MEMORY_SCOPE_AGENT); }
; DI void xcd_barrier_complete(unsigned* bar, unsigned x, unsigned& nloc, unsigned& nx) {
;   const unsigned G = gridDim.x * gridDim.y * gridDim.z;
;   unsigned sum, cnt, mine, sp = 0u;
;   for (;;) {
;     sum = 0u; cnt = 0u; mine = 0u;
; #pragma unroll
;     for (unsigned j = 0; j < 16; ++j) { const unsigned c = xb_ld(&bar[XB_XCNT(j)]); sum += c; cnt += (c > 0u) ? 1u : 0u; mine = (j == x) ? c : mine; }
; DI void xcd_barrier(const XcdBarrier& b) {
;     ...
;   if (threadIdx.x == 0) {
;     unsigned* bar = b.bar;
;     __builtin_amdgcn_s_waitcnt(0);
;     unsigned nloc = b.st[0], nx = b.st[1];
;     if (nloc == 0u) { xcd_barrier_complete(bar, b.x, nloc, nx); b.st[0] = nloc; b.st[1] = nx; }
.Lfp_fb_12:
	v_mov_b32_e32 v0, 0
	s_waitcnt vmcnt(0) expcnt(0) lgkmcnt(0)
	ds_read_b32 v2, v0 offset:256
	ds_read_b32 v1, v0 offset:260
	s_waitcnt lgkmcnt(1)
	v_cmp_ne_u32_e32 vcc, 0, v2
	s_cbranch_vccnz .LBB0_1407
	v_readlane_b32 s2, v254, 4
	s_mul_i32 s4, s89, s2
	s_add_u32 s2, s86, 0xbfa0200
	s_addc_u32 s3, s87, 0
	s_add_u32 s6, s86, 0xbfa0400
	s_addc_u32 s7, s87, 0
	s_add_u32 s8, s86, 0xbfa0500
	s_addc_u32 s9, s87, 0
	s_add_u32 s10, s86, 0xbfa0600
	s_addc_u32 s11, s87, 0
	s_add_u32 s12, s86, 0xbfa0700
	s_addc_u32 s13, s87, 0
	s_add_u32 s14, s86, 0xbfa0800
	s_addc_u32 s15, s87, 0
	s_add_u32 s16, s86, 0xbfa0900
	s_addc_u32 s17, s87, 0
	s_add_u32 s18, s86, 0xbfa0a00
	s_addc_u32 s19, s87, 0
	s_add_u32 s20, s86, 0xbfa0b00
	s_addc_u32 s21, s87, 0
	s_add_u32 s22, s86, 0xbfa0c00
	s_addc_u32 s23, s87, 0
	s_add_u32 s24, s86, 0xbfa0d00
	s_addc_u32 s25, s87, 0
	s_add_u32 s26, s86, 0xbfa0e00
	s_addc_u32 s27, s87, 0
	s_add_u32 s28, s86, 0xbfa0f00
	s_addc_u32 s29, s87, 0
	s_add_u32 s30, s86, 0xbfa1000
	s_addc_u32 s31, s87, 0
	s_add_u32 s34, s86, 0xbfa1100
	s_addc_u32 s35, s87, 0
	s_add_u32 s36, s86, 0xbfa1200
	s_addc_u32 s37, s87, 0
	s_add_u32 s38, s86, 0xbfa1300
	s_mul_i32 s4, s4, s88
	s_addc_u32 s39, s87, 0
	s_mov_b32 s5, 1
	s_branch .LBB0_1395
